# cache prefetch loads ahead of compiler-serialized load-wait chains (hyena prompt conv3 rows, hyena sample filter taps, attn_finish gates, fnet rows)
# speedup vs baseline: 1.0660x; 1.0660x over previous
.LBB0_118:
	v_lshl_add_u64 v[250:251], s[24:25], 1, v[10:11]
	s_mov_b32 s100, 0x1000
	s_mov_b32 s101, 0
	v_lshl_add_u64 v[252:253], v[250:251], 0, s[100:101]
	global_load_ushort v255, v[250:251], off
	global_load_ushort v255, v[250:251], off offset:512
	global_load_ushort v255, v[250:251], off offset:1024
	global_load_ushort v255, v[250:251], off offset:1536
	global_load_ushort v255, v[250:251], off offset:2048
	global_load_ushort v255, v[250:251], off offset:2560
	global_load_ushort v255, v[250:251], off offset:3072
	global_load_ushort v255, v[250:251], off offset:3584
	global_load_ushort v255, v[252:253], off
	global_load_ushort v255, v[252:253], off offset:512
	global_load_ushort v255, v[252:253], off offset:1024
	global_load_ushort v255, v[252:253], off offset:1536
	global_load_ushort v255, v[252:253], off offset:2048
	global_load_ushort v255, v[252:253], off offset:2560
	global_load_ushort v255, v[252:253], off offset:3072
	global_load_ushort v255, v[252:253], off offset:3584
	s_lshl_b64 s[100:101], s[24:25], 1
	s_add_u32 s100, s1, s100
	s_addc_u32 s101, s94, s101
	v_lshl_add_u64 v[250:251], v[12:13], 1, s[100:101]
	s_add_u32 s100, s100, 0x1000
	s_addc_u32 s101, s101, 0
	v_lshl_add_u64 v[252:253], v[12:13], 1, s[100:101]
	global_load_ushort v255, v[250:251], off
	global_load_ushort v255, v[250:251], off offset:512
	global_load_ushort v255, v[250:251], off offset:1024
	global_load_ushort v255, v[250:251], off offset:1536
	global_load_ushort v255, v[250:251], off offset:2048
	global_load_ushort v255, v[250:251], off offset:2560
	global_load_ushort v255, v[250:251], off offset:3072
	global_load_ushort v255, v[250:251], off offset:3584
	global_load_ushort v255, v[252:253], off
	global_load_ushort v255, v[252:253], off offset:512
	global_load_ushort v255, v[252:253], off offset:1024
	global_load_ushort v255, v[252:253], off offset:1536
	global_load_ushort v255, v[252:253], off offset:2048
	global_load_ushort v255, v[252:253], off offset:2560
	global_load_ushort v255, v[252:253], off offset:3072
	global_load_ushort v255, v[252:253], off offset:3584
	s_lshl_b64 s[100:101], s[24:25], 1
	s_add_u32 s100, s28, s100
	s_addc_u32 s101, s29, s101
	v_lshl_add_u64 v[250:251], v[12:13], 1, s[100:101]
	s_add_u32 s100, s100, 0x1000
	s_addc_u32 s101, s101, 0
	v_lshl_add_u64 v[252:253], v[12:13], 1, s[100:101]
	global_load_ushort v255, v[250:251], off
	global_load_ushort v255, v[250:251], off offset:512
	global_load_ushort v255, v[250:251], off offset:1024
	global_load_ushort v255, v[250:251], off offset:1536
	global_load_ushort v255, v[250:251], off offset:2048
	global_load_ushort v255, v[250:251], off offset:2560
	global_load_ushort v255, v[250:251], off offset:3072
	global_load_ushort v255, v[250:251], off offset:3584
	global_load_ushort v255, v[252:253], off
	global_load_ushort v255, v[252:253], off offset:512
	global_load_ushort v255, v[252:253], off offset:1024
	global_load_ushort v255, v[252:253], off offset:1536
	global_load_ushort v255, v[252:253], off offset:2048
	global_load_ushort v255, v[252:253], off offset:2560
	global_load_ushort v255, v[252:253], off offset:3072
	global_load_ushort v255, v[252:253], off offset:3584
	s_or_b32 s68, s24, 0x800
	s_mov_b32 s69, s25
	s_and_b64 vcc, exec, s[50:51]
	v_lshl_add_u64 v[80:81], s[24:25], 1, v[10:11]
	v_lshl_add_u64 v[106:107], s[68:69], 1, v[10:11]
	s_mov_b64 s[52:53], -1
	s_cbranch_vccz .LBB0_120
	global_load_ushort v1, v[106:107], off
	global_load_ushort v2, v[80:81], off
	s_mov_b64 s[52:53], 0
	s_waitcnt vmcnt(1)
	v_lshlrev_b32_e32 v113, 16, v1
	s_waitcnt vmcnt(0)
	v_lshlrev_b32_e32 v112, 16, v2

.LBB0_314:
	s_add_u32 s22, s0, s10
	s_addc_u32 s23, 0, s11
	s_lshl_b64 s[22:23], s[22:23], 14
	v_readlane_b32 s6, v246, 14
	v_readlane_b32 s7, v246, 15
	s_add_u32 s66, s6, s22
	s_addc_u32 s67, s7, s23
	s_or_b32 s1, s0, 0x800
	s_add_u32 s22, s1, s10
	s_addc_u32 s23, 0, s11
	s_lshl_b64 s[22:23], s[22:23], 14
	s_add_u32 s34, s6, s22
	s_addc_u32 s35, s7, s23
	v_lshlrev_b32_e32 v250, 2, v122
	v_sub_u32_e32 v251, 0x4000, v250
	global_load_dword v255, v250, s[66:67]
	global_load_dword v255, v250, s[66:67] offset:1024
	global_load_dword v255, v250, s[66:67] offset:2048
	global_load_dword v255, v250, s[66:67] offset:3072
	v_add_u32_e32 v250, 0x1000, v250
	global_load_dword v255, v250, s[66:67]
	global_load_dword v255, v250, s[66:67] offset:1024
	global_load_dword v255, v250, s[66:67] offset:2048
	global_load_dword v255, v250, s[66:67] offset:3072
	v_add_u32_e32 v250, 0x1000, v250
	global_load_dword v255, v250, s[66:67]
	global_load_dword v255, v250, s[66:67] offset:1024
	global_load_dword v255, v250, s[66:67] offset:2048
	global_load_dword v255, v250, s[66:67] offset:3072
	v_add_u32_e32 v250, 0x1000, v250
	global_load_dword v255, v250, s[66:67]
	global_load_dword v255, v250, s[66:67] offset:1024
	global_load_dword v255, v250, s[66:67] offset:2048
	global_load_dword v255, v250, s[66:67] offset:3072
	global_load_dword v255, v251, s[34:35]
	global_load_dword v255, v251, s[34:35] offset:-1024
	global_load_dword v255, v251, s[34:35] offset:-2048
	global_load_dword v255, v251, s[34:35] offset:-3072
	v_add_u32_e32 v251, 0xfffff000, v251
	global_load_dword v255, v251, s[34:35]
	global_load_dword v255, v251, s[34:35] offset:-1024
	global_load_dword v255, v251, s[34:35] offset:-2048
	global_load_dword v255, v251, s[34:35] offset:-3072
	v_add_u32_e32 v251, 0xfffff000, v251
	global_load_dword v255, v251, s[34:35]
	global_load_dword v255, v251, s[34:35] offset:-1024
	global_load_dword v255, v251, s[34:35] offset:-2048
	global_load_dword v255, v251, s[34:35] offset:-3072
	v_add_u32_e32 v251, 0xfffff000, v251
	global_load_dword v255, v251, s[34:35]
	global_load_dword v255, v251, s[34:35] offset:-1024
	global_load_dword v255, v251, s[34:35] offset:-2048
	global_load_dword v255, v251, s[34:35] offset:-3072
	s_add_i32 s22, s0, s10
	s_ashr_i32 s23, s22, 31
	v_readlane_b32 s36, v245, 46
	s_lshl_b64 s[22:23], s[22:23], 2
	v_readlane_b32 s42, v245, 52
	v_readlane_b32 s37, v245, 47
	v_readlane_b32 s43, v245, 53
	s_add_u32 s36, s42, s22
	v_readlane_b32 s38, v245, 48
	v_readlane_b32 s39, v245, 49
	v_readlane_b32 s40, v245, 50
	v_readlane_b32 s41, v245, 51
	s_addc_u32 s37, s43, s23
	s_add_i32 s0, s13, s0
	global_load_dword v114, v0, s[36:37]
	s_ashr_i32 s1, s0, 31
	v_readlane_b32 s36, v245, 56
	s_lshl_b64 s[0:1], s[0:1], 2
	v_readlane_b32 s40, v245, 60
	v_readlane_b32 s37, v245, 57
	v_readlane_b32 s41, v245, 61
	s_add_u32 s36, s40, s0
	v_readlane_b32 s42, v245, 62
	s_addc_u32 s37, s41, s1
	v_readlane_b32 s43, v245, 63
	s_add_u32 s0, s42, s0
	s_addc_u32 s1, s43, s1
	s_add_u32 s22, s4, s22
	s_addc_u32 s23, s5, s23
	global_load_dword v6, v0, s[16:17]
	global_load_dword v8, v0, s[18:19]
	global_load_dword v10, v0, s[8:9]
	global_load_dword v12, v0, s[14:15]
	global_load_dword v123, v0, s[36:37]
	global_load_dword v124, v186, s[36:37]
	global_load_dword v125, v187, s[36:37]
	global_load_dword v126, v0, s[0:1]
	global_load_dword v1, v0, s[22:23]
	v_readlane_b32 s38, v245, 58
	v_readlane_b32 s39, v245, 59
	v_readlane_b32 s44, v244, 0
	v_readlane_b32 s45, v244, 1
	v_readlane_b32 s46, v244, 2
	v_readlane_b32 s47, v244, 3
	v_readlane_b32 s48, v244, 4
	v_readlane_b32 s49, v244, 5
	v_readlane_b32 s50, v244, 6
	v_readlane_b32 s51, v244, 7
	s_waitcnt vmcnt(0)
	v_add_f32_e32 v1, 0x358637bd, v1
	v_div_scale_f32 v2, s[0:1], v1, v1, 1.0
	v_rcp_f32_e32 v3, v2
	s_nop 0
	v_fma_f32 v4, -v2, v3, 1.0
	v_fmac_f32_e32 v3, v4, v3
	v_div_scale_f32 v4, vcc, 1.0, v1, 1.0
	v_mul_f32_e32 v5, v4, v3
	v_fma_f32 v7, -v2, v5, v4
	v_fmac_f32_e32 v5, v7, v3
	v_fma_f32 v2, -v2, v5, v4
	v_div_fmas_f32 v2, v2, v3, v5
	v_div_fixup_f32 v1, v2, v1, 1.0
	v_mov_b32_e32 v2, v122
	v_mov_b32_e32 v3, v0
	s_nop 0
	v_lshl_add_u64 v[4:5], v[2:3], 2, s[66:67]
	global_load_dword v3, v[4:5], off
	v_cmp_eq_u32_e32 vcc, 0, v2
	v_cmp_ne_u32_e64 s[0:1], 0, v2
	v_mov_b32_e32 v4, 0
	v_mov_b32_e32 v5, 0
	s_and_saveexec_b64 s[36:37], s[0:1]
	s_cbranch_execz .LBB0_316
	v_sub_u32_e32 v14, 0x1000, v2
	v_mov_b32_e32 v15, v0
	v_lshl_add_u64 v[14:15], v[14:15], 2, s[34:35]
	global_load_dword v5, v[14:15], off
	s_waitcnt vmcnt(0)
	v_mul_f32_e32 v5, v1, v5

.LBB0_412:
	v_lshlrev_b32_e32 v250, 2, v122
	v_sub_u32_e32 v251, 0x4000, v250
	global_load_dword v255, v250, s[66:67]
	global_load_dword v255, v250, s[66:67] offset:1024
	global_load_dword v255, v250, s[66:67] offset:2048
	global_load_dword v255, v250, s[66:67] offset:3072
	v_add_u32_e32 v250, 0x1000, v250
	global_load_dword v255, v250, s[66:67]
	global_load_dword v255, v250, s[66:67] offset:1024
	global_load_dword v255, v250, s[66:67] offset:2048
	global_load_dword v255, v250, s[66:67] offset:3072
	v_add_u32_e32 v250, 0x1000, v250
	global_load_dword v255, v250, s[66:67]
	global_load_dword v255, v250, s[66:67] offset:1024
	global_load_dword v255, v250, s[66:67] offset:2048
	global_load_dword v255, v250, s[66:67] offset:3072
	v_add_u32_e32 v250, 0x1000, v250
	global_load_dword v255, v250, s[66:67]
	global_load_dword v255, v250, s[66:67] offset:1024
	global_load_dword v255, v250, s[66:67] offset:2048
	global_load_dword v255, v250, s[66:67] offset:3072
	global_load_dword v255, v251, s[34:35]
	global_load_dword v255, v251, s[34:35] offset:-1024
	global_load_dword v255, v251, s[34:35] offset:-2048
	global_load_dword v255, v251, s[34:35] offset:-3072
	v_add_u32_e32 v251, 0xfffff000, v251
	global_load_dword v255, v251, s[34:35]
	global_load_dword v255, v251, s[34:35] offset:-1024
	global_load_dword v255, v251, s[34:35] offset:-2048
	global_load_dword v255, v251, s[34:35] offset:-3072
	v_add_u32_e32 v251, 0xfffff000, v251
	global_load_dword v255, v251, s[34:35]
	global_load_dword v255, v251, s[34:35] offset:-1024
	global_load_dword v255, v251, s[34:35] offset:-2048
	global_load_dword v255, v251, s[34:35] offset:-3072
	v_add_u32_e32 v251, 0xfffff000, v251
	global_load_dword v255, v251, s[34:35]
	global_load_dword v255, v251, s[34:35] offset:-1024
	global_load_dword v255, v251, s[34:35] offset:-2048
	global_load_dword v255, v251, s[34:35] offset:-3072
	global_load_dword v1, v0, s[22:23]
	v_mov_b32_e32 v42, 0
	v_mov_b32_e32 v43, 0
	s_waitcnt vmcnt(0)
	v_add_f32_e32 v1, 0x358637bd, v1
	v_div_scale_f32 v2, s[0:1], v1, v1, 1.0
	v_rcp_f32_e32 v3, v2
	s_nop 0
	v_fma_f32 v4, -v2, v3, 1.0
	v_fmac_f32_e32 v3, v4, v3
	v_div_scale_f32 v4, vcc, 1.0, v1, 1.0
	v_mul_f32_e32 v5, v4, v3
	v_fma_f32 v14, -v2, v5, v4
	v_fmac_f32_e32 v5, v14, v3
	v_fma_f32 v2, -v2, v5, v4
	v_div_fmas_f32 v2, v2, v3, v5
	v_div_fixup_f32 v1, v2, v1, 1.0
	v_mov_b32_e32 v2, v122
	v_mov_b32_e32 v3, v0
	s_nop 0
	v_lshl_add_u64 v[4:5], v[2:3], 2, s[66:67]
	global_load_dword v3, v[4:5], off
	v_cmp_eq_u32_e32 vcc, 0, v2
	v_cmp_ne_u32_e64 s[0:1], 0, v2
	s_and_saveexec_b64 s[22:23], s[0:1]
	s_cbranch_execz .LBB0_414
	v_sub_u32_e32 v4, 0x1000, v2
	v_mov_b32_e32 v5, v0
	v_lshl_add_u64 v[4:5], v[4:5], 2, s[34:35]
	global_load_dword v4, v[4:5], off
	s_waitcnt vmcnt(0)
	v_mul_f32_e32 v43, v1, v4

.LBB0_615:
	v_and_b32_e32 v19, 64, v195
	v_readlane_b32 s0, v246, 36
	v_xor_b32_e32 v1, 32, v195
	v_add_u32_e32 v19, 64, v19
	v_lshlrev_b64 v[22:23], 1, v[114:115]
	v_readlane_b32 s1, v246, 37
	v_or_b32_e32 v18, s6, v18
	v_cmp_lt_i32_e32 vcc, v1, v19
	v_lshl_add_u64 v[20:21], s[0:1], 0, v[22:23]
	v_mul_i32_i24_e32 v18, 0x14000, v18
	v_mov_b32_e32 v19, v0
	v_lshl_add_u64 v[20:21], v[20:21], 0, v[18:19]
	s_mov_b32 s101, 0
	s_mov_b32 s100, 0x14000
	v_lshl_add_u64 v[250:251], v[20:21], 0, s[100:101]
	global_load_ushort v255, v[250:251], off
	s_mov_b32 s100, 0x28000
	v_lshl_add_u64 v[252:253], v[20:21], 0, s[100:101]
	global_load_ushort v255, v[252:253], off
	s_mov_b32 s100, 0x3c000
	v_lshl_add_u64 v[250:251], v[20:21], 0, s[100:101]
	global_load_ushort v255, v[250:251], off
	s_mov_b32 s100, 0xa0000
	v_lshl_add_u64 v[252:253], v[20:21], 0, s[100:101]
	global_load_ushort v255, v[252:253], off
	s_mov_b32 s100, 0xb4000
	v_lshl_add_u64 v[250:251], v[20:21], 0, s[100:101]
	global_load_ushort v255, v[250:251], off
	s_mov_b32 s100, 0xc8000
	v_lshl_add_u64 v[252:253], v[20:21], 0, s[100:101]
	global_load_ushort v255, v[252:253], off
	s_mov_b32 s100, 0xdc000
	v_lshl_add_u64 v[250:251], v[20:21], 0, s[100:101]
	global_load_ushort v255, v[250:251], off
	s_mov_b32 s100, 0x140000
	v_lshl_add_u64 v[252:253], v[20:21], 0, s[100:101]
	global_load_ushort v255, v[252:253], off
	s_mov_b32 s100, 0x154000
	v_lshl_add_u64 v[250:251], v[20:21], 0, s[100:101]
	global_load_ushort v255, v[250:251], off
	s_mov_b32 s100, 0x168000
	v_lshl_add_u64 v[252:253], v[20:21], 0, s[100:101]
	global_load_ushort v255, v[252:253], off
	s_mov_b32 s100, 0x17c000
	v_lshl_add_u64 v[250:251], v[20:21], 0, s[100:101]
	global_load_ushort v255, v[250:251], off
	s_mov_b32 s100, 0x1e0000
	v_lshl_add_u64 v[252:253], v[20:21], 0, s[100:101]
	global_load_ushort v255, v[252:253], off
	s_mov_b32 s100, 0x1f4000
	v_lshl_add_u64 v[250:251], v[20:21], 0, s[100:101]
	global_load_ushort v255, v[250:251], off
	s_mov_b32 s100, 0x208000
	v_lshl_add_u64 v[252:253], v[20:21], 0, s[100:101]
	global_load_ushort v255, v[252:253], off
	s_mov_b32 s100, 0x21c000
	v_lshl_add_u64 v[250:251], v[20:21], 0, s[100:101]
	global_load_ushort v255, v[250:251], off
	s_mov_b32 s100, 0x280000
	v_lshl_add_u64 v[252:253], v[20:21], 0, s[100:101]
	global_load_ushort v255, v[252:253], off
	s_mov_b32 s100, 0x294000
	v_lshl_add_u64 v[250:251], v[20:21], 0, s[100:101]
	global_load_ushort v255, v[250:251], off
	s_mov_b32 s100, 0x2a8000
	v_lshl_add_u64 v[252:253], v[20:21], 0, s[100:101]
	global_load_ushort v255, v[252:253], off
	s_mov_b32 s100, 0x2bc000
	v_lshl_add_u64 v[250:251], v[20:21], 0, s[100:101]
	global_load_ushort v255, v[250:251], off
	s_mov_b32 s100, 0x320000
	v_lshl_add_u64 v[252:253], v[20:21], 0, s[100:101]
	global_load_ushort v255, v[252:253], off
	s_mov_b32 s100, 0x334000
	v_lshl_add_u64 v[250:251], v[20:21], 0, s[100:101]
	global_load_ushort v255, v[250:251], off
	s_mov_b32 s100, 0x348000
	v_lshl_add_u64 v[252:253], v[20:21], 0, s[100:101]
	global_load_ushort v255, v[252:253], off
	s_mov_b32 s100, 0x35c000
	v_lshl_add_u64 v[250:251], v[20:21], 0, s[100:101]
	global_load_ushort v255, v[250:251], off
	s_mov_b32 s100, 0x3c0000
	v_lshl_add_u64 v[252:253], v[20:21], 0, s[100:101]
	global_load_ushort v255, v[252:253], off
	s_mov_b32 s100, 0x3d4000
	v_lshl_add_u64 v[250:251], v[20:21], 0, s[100:101]
	global_load_ushort v255, v[250:251], off
	s_mov_b32 s100, 0x3e8000
	v_lshl_add_u64 v[252:253], v[20:21], 0, s[100:101]
	global_load_ushort v255, v[252:253], off
	s_mov_b32 s100, 0x3fc000
	v_lshl_add_u64 v[250:251], v[20:21], 0, s[100:101]
	global_load_ushort v255, v[250:251], off
	s_mov_b32 s100, 0x460000
	v_lshl_add_u64 v[252:253], v[20:21], 0, s[100:101]
	global_load_ushort v255, v[252:253], off
	s_mov_b32 s100, 0x474000
	v_lshl_add_u64 v[250:251], v[20:21], 0, s[100:101]
	global_load_ushort v255, v[250:251], off
	s_mov_b32 s100, 0x488000
	v_lshl_add_u64 v[252:253], v[20:21], 0, s[100:101]
	global_load_ushort v255, v[252:253], off
	s_mov_b32 s100, 0x49c000
	v_lshl_add_u64 v[250:251], v[20:21], 0, s[100:101]
	global_load_ushort v255, v[250:251], off
	global_load_ushort v24, v[20:21], off
	v_cndmask_b32_e32 v1, v195, v1, vcc
	v_lshlrev_b32_e32 v1, 2, v1
	ds_bpermute_b32 v1, v1, v66
	v_lshl_add_u64 v[18:19], s[68:69], 0, v[18:19]
	v_lshl_add_u64 v[18:19], v[18:19], 0, v[22:23]
	s_movk_i32 s77, 0xc00
	s_waitcnt lgkmcnt(0)
	v_add_f32_e32 v1, v66, v1
	v_rcp_f32_e32 v1, v1
	s_waitcnt vmcnt(0)
	v_lshlrev_b32_e32 v24, 16, v24
	v_mul_f32_e32 v25, v50, v1
	v_mul_f32_e32 v24, v25, v24
	v_cvt_pk_bf16_f32 v24, v24, s0
	s_mov_b32 s0, 0xd84a000
	v_add_co_u32_e32 v22, vcc, s0, v18
	v_mul_f32_e32 v2, v2, v1
	s_nop 0
	v_addc_co_u32_e32 v23, vcc, 0, v19, vcc
	global_store_short v[22:23], v24, off
	v_add_co_u32_e32 v22, vcc, s97, v20
	v_mul_f32_e32 v3, v3, v1
	s_nop 0
	v_addc_co_u32_e32 v23, vcc, 0, v21, vcc
	global_load_ushort v22, v[22:23], off
	v_mul_f32_e32 v23, v51, v1
	s_waitcnt vmcnt(0)
	v_lshlrev_b32_e32 v22, 16, v22
	v_mul_f32_e32 v22, v23, v22
	v_cvt_pk_bf16_f32 v24, v22, s0
	s_mov_b32 s0, 0xd85e000
	v_add_co_u32_e32 v22, vcc, s0, v18
	s_mov_b32 s0, 0x28000
	s_nop 0
	v_addc_co_u32_e32 v23, vcc, 0, v19, vcc
	global_store_short v[22:23], v24, off
	v_add_co_u32_e32 v22, vcc, s0, v20
	s_nop 1
	v_addc_co_u32_e32 v23, vcc, 0, v21, vcc
	global_load_ushort v22, v[22:23], off
	v_mul_f32_e32 v23, v52, v1
	s_waitcnt vmcnt(0)
	v_lshlrev_b32_e32 v22, 16, v22
	v_mul_f32_e32 v22, v23, v22
	v_cvt_pk_bf16_f32 v24, v22, s0
	s_mov_b32 s0, 0xd872000
	v_add_co_u32_e32 v22, vcc, s0, v18
	s_mov_b32 s0, 0x3c000
	s_nop 0
	v_addc_co_u32_e32 v23, vcc, 0, v19, vcc
	global_store_short v[22:23], v24, off
	v_add_co_u32_e32 v22, vcc, s0, v20
	s_nop 1
	v_addc_co_u32_e32 v23, vcc, 0, v21, vcc
	global_load_ushort v22, v[22:23], off
	v_mul_f32_e32 v23, v53, v1
	s_waitcnt vmcnt(0)
	v_lshlrev_b32_e32 v22, 16, v22
	v_mul_f32_e32 v22, v23, v22
	v_cvt_pk_bf16_f32 v24, v22, s0
	s_mov_b32 s0, 0xd886000
	v_add_co_u32_e32 v22, vcc, s0, v18
	s_mov_b32 s0, 0xa0000
	s_nop 0
	v_addc_co_u32_e32 v23, vcc, 0, v19, vcc
	global_store_short v[22:23], v24, off
	v_add_co_u32_e32 v22, vcc, s0, v20
	s_nop 1
	v_addc_co_u32_e32 v23, vcc, 0, v21, vcc
	global_load_ushort v22, v[22:23], off
	v_mul_f32_e32 v23, v54, v1
	s_waitcnt vmcnt(0)
	v_lshlrev_b32_e32 v22, 16, v22
	v_mul_f32_e32 v22, v23, v22
	v_cvt_pk_bf16_f32 v24, v22, s0
	s_mov_b32 s0, 0xd8ea000
	v_add_co_u32_e32 v22, vcc, s0, v18
	s_mov_b32 s0, 0xb4000
	s_nop 0
	v_addc_co_u32_e32 v23, vcc, 0, v19, vcc
	global_store_short v[22:23], v24, off
	v_add_co_u32_e32 v22, vcc, s0, v20
	s_nop 1
	v_addc_co_u32_e32 v23, vcc, 0, v21, vcc
	global_load_ushort v22, v[22:23], off
	v_mul_f32_e32 v23, v55, v1
	s_waitcnt vmcnt(0)
	v_lshlrev_b32_e32 v22, 16, v22
	v_mul_f32_e32 v22, v23, v22
	v_cvt_pk_bf16_f32 v24, v22, s0
	s_mov_b32 s0, 0xd8fe000
	v_add_co_u32_e32 v22, vcc, s0, v18
	s_mov_b32 s0, 0xc8000
	s_nop 0
	v_addc_co_u32_e32 v23, vcc, 0, v19, vcc
	global_store_short v[22:23], v24, off
	v_add_co_u32_e32 v22, vcc, s0, v20
	s_nop 1
	v_addc_co_u32_e32 v23, vcc, 0, v21, vcc
	global_load_ushort v22, v[22:23], off
	v_mul_f32_e32 v23, v56, v1
	s_waitcnt vmcnt(0)
	v_lshlrev_b32_e32 v22, 16, v22
	v_mul_f32_e32 v22, v23, v22
	v_cvt_pk_bf16_f32 v24, v22, s0
	s_mov_b32 s0, 0xd912000
	v_add_co_u32_e32 v22, vcc, s0, v18
	s_mov_b32 s0, 0xdc000
	s_nop 0
	v_addc_co_u32_e32 v23, vcc, 0, v19, vcc
	global_store_short v[22:23], v24, off
	v_add_co_u32_e32 v22, vcc, s0, v20
	s_nop 1
	v_addc_co_u32_e32 v23, vcc, 0, v21, vcc
	global_load_ushort v22, v[22:23], off
	v_mul_f32_e32 v23, v57, v1
	s_waitcnt vmcnt(0)
	v_lshlrev_b32_e32 v22, 16, v22
	v_mul_f32_e32 v22, v23, v22
	v_cvt_pk_bf16_f32 v24, v22, s0
	s_mov_b32 s0, 0xd926000
	v_add_co_u32_e32 v22, vcc, s0, v18
	s_mov_b32 s0, 0x140000
	s_nop 0
	v_addc_co_u32_e32 v23, vcc, 0, v19, vcc
	global_store_short v[22:23], v24, off
	v_add_co_u32_e32 v22, vcc, s0, v20
	s_nop 1
	v_addc_co_u32_e32 v23, vcc, 0, v21, vcc
	global_load_ushort v22, v[22:23], off
	v_mul_f32_e32 v23, v58, v1
	s_waitcnt vmcnt(0)
	v_lshlrev_b32_e32 v22, 16, v22
	v_mul_f32_e32 v22, v23, v22
	v_cvt_pk_bf16_f32 v24, v22, s0
	s_mov_b32 s0, 0xd98a000
	v_add_co_u32_e32 v22, vcc, s0, v18
	s_mov_b32 s0, 0x154000
	s_nop 0
	v_addc_co_u32_e32 v23, vcc, 0, v19, vcc
	global_store_short v[22:23], v24, off
	v_add_co_u32_e32 v22, vcc, s0, v20
	s_nop 1
	v_addc_co_u32_e32 v23, vcc, 0, v21, vcc
	global_load_ushort v22, v[22:23], off
	v_mul_f32_e32 v23, v59, v1
	s_waitcnt vmcnt(0)
	v_lshlrev_b32_e32 v22, 16, v22
	v_mul_f32_e32 v22, v23, v22
	v_cvt_pk_bf16_f32 v24, v22, s0
	s_mov_b32 s0, 0xd99e000
	v_add_co_u32_e32 v22, vcc, s0, v18
	s_mov_b32 s0, 0x168000
	s_nop 0
	v_addc_co_u32_e32 v23, vcc, 0, v19, vcc
	global_store_short v[22:23], v24, off
	v_add_co_u32_e32 v22, vcc, s0, v20
	s_nop 1
	v_addc_co_u32_e32 v23, vcc, 0, v21, vcc
	global_load_ushort v22, v[22:23], off
	v_mul_f32_e32 v23, v60, v1
	s_waitcnt vmcnt(0)
	v_lshlrev_b32_e32 v22, 16, v22
	v_mul_f32_e32 v22, v23, v22
	v_cvt_pk_bf16_f32 v24, v22, s0
	s_mov_b32 s0, 0xd9b2000
	v_add_co_u32_e32 v22, vcc, s0, v18
	s_mov_b32 s0, 0x17c000
	s_nop 0
	v_addc_co_u32_e32 v23, vcc, 0, v19, vcc
	global_store_short v[22:23], v24, off
	v_add_co_u32_e32 v22, vcc, s0, v20
	s_nop 1
	v_addc_co_u32_e32 v23, vcc, 0, v21, vcc
	global_load_ushort v22, v[22:23], off
	v_mul_f32_e32 v23, v61, v1
	s_waitcnt vmcnt(0)
	v_lshlrev_b32_e32 v22, 16, v22
	v_mul_f32_e32 v22, v23, v22
	v_cvt_pk_bf16_f32 v24, v22, s0
	s_mov_b32 s0, 0xd9c6000
	v_add_co_u32_e32 v22, vcc, s0, v18
	s_mov_b32 s0, 0x1e0000
	s_nop 0
	v_addc_co_u32_e32 v23, vcc, 0, v19, vcc
	global_store_short v[22:23], v24, off
	v_add_co_u32_e32 v22, vcc, s0, v20
	s_nop 1
	v_addc_co_u32_e32 v23, vcc, 0, v21, vcc
	global_load_ushort v22, v[22:23], off
	v_mul_f32_e32 v23, v62, v1
	s_waitcnt vmcnt(0)
	v_lshlrev_b32_e32 v22, 16, v22
	v_mul_f32_e32 v22, v23, v22
	v_cvt_pk_bf16_f32 v24, v22, s0
	s_mov_b32 s0, 0xda2a000
	v_add_co_u32_e32 v22, vcc, s0, v18
	s_mov_b32 s0, 0x1f4000
	s_nop 0
	v_addc_co_u32_e32 v23, vcc, 0, v19, vcc
	global_store_short v[22:23], v24, off
	v_add_co_u32_e32 v22, vcc, s0, v20
	s_nop 1
	v_addc_co_u32_e32 v23, vcc, 0, v21, vcc
	global_load_ushort v22, v[22:23], off
	v_mul_f32_e32 v23, v63, v1
	s_waitcnt vmcnt(0)
	v_lshlrev_b32_e32 v22, 16, v22
	v_mul_f32_e32 v22, v23, v22
	v_cvt_pk_bf16_f32 v24, v22, s0
	s_mov_b32 s0, 0xda3e000
	v_add_co_u32_e32 v22, vcc, s0, v18
	s_mov_b32 s0, 0x208000
	s_nop 0
	v_addc_co_u32_e32 v23, vcc, 0, v19, vcc
	global_store_short v[22:23], v24, off
	v_add_co_u32_e32 v22, vcc, s0, v20
	s_nop 1
	v_addc_co_u32_e32 v23, vcc, 0, v21, vcc
	global_load_ushort v22, v[22:23], off
	v_mul_f32_e32 v23, v64, v1
	s_waitcnt vmcnt(0)
	v_lshlrev_b32_e32 v22, 16, v22
	v_mul_f32_e32 v22, v23, v22
	v_cvt_pk_bf16_f32 v24, v22, s0
	s_mov_b32 s0, 0xda52000
	v_add_co_u32_e32 v22, vcc, s0, v18
	s_mov_b32 s0, 0x21c000
	s_nop 0
	v_addc_co_u32_e32 v23, vcc, 0, v19, vcc
	global_store_short v[22:23], v24, off
	v_add_co_u32_e32 v22, vcc, s0, v20
	s_nop 1
	v_addc_co_u32_e32 v23, vcc, 0, v21, vcc
	global_load_ushort v22, v[22:23], off
	v_mul_f32_e32 v23, v65, v1
	s_waitcnt vmcnt(0)
	v_lshlrev_b32_e32 v22, 16, v22
	v_mul_f32_e32 v22, v23, v22
	v_cvt_pk_bf16_f32 v24, v22, s0
	s_mov_b32 s0, 0xda66000
	v_add_co_u32_e32 v22, vcc, s0, v18
	s_mov_b32 s0, 0x280000
	s_nop 0
	v_addc_co_u32_e32 v23, vcc, 0, v19, vcc
	global_store_short v[22:23], v24, off
	v_add_co_u32_e32 v22, vcc, s0, v20
	s_nop 1
	v_addc_co_u32_e32 v23, vcc, 0, v21, vcc
	global_load_ushort v22, v[22:23], off
	s_waitcnt vmcnt(0)
	v_lshlrev_b32_e32 v22, 16, v22
	v_mul_f32_e32 v2, v2, v22
	v_cvt_pk_bf16_f32 v2, v2, s0
	s_mov_b32 s0, 0xdaca000
	v_add_co_u32_e32 v22, vcc, s0, v18
	s_mov_b32 s0, 0x294000
	s_nop 0
	v_addc_co_u32_e32 v23, vcc, 0, v19, vcc
	global_store_short v[22:23], v2, off
	v_add_co_u32_e32 v22, vcc, s0, v20
	s_nop 1
	v_addc_co_u32_e32 v23, vcc, 0, v21, vcc
	global_load_ushort v2, v[22:23], off
	s_waitcnt vmcnt(0)
	v_lshlrev_b32_e32 v2, 16, v2
	v_mul_f32_e32 v2, v3, v2
	v_cvt_pk_bf16_f32 v22, v2, s0
	s_mov_b32 s0, 0xdade000
	v_add_co_u32_e32 v2, vcc, s0, v18
	s_mov_b32 s0, 0x2a8000
	s_nop 0
	v_addc_co_u32_e32 v3, vcc, 0, v19, vcc
	global_store_short v[2:3], v22, off
	v_add_co_u32_e32 v2, vcc, s0, v20
	s_nop 1
	v_addc_co_u32_e32 v3, vcc, 0, v21, vcc
	global_load_ushort v2, v[2:3], off
	v_mul_f32_e32 v3, v4, v1
	s_waitcnt vmcnt(0)
	v_lshlrev_b32_e32 v2, 16, v2
	v_mul_f32_e32 v2, v3, v2
	v_cvt_pk_bf16_f32 v4, v2, s0
	s_mov_b32 s0, 0xdaf2000
	v_add_co_u32_e32 v2, vcc, s0, v18
	s_mov_b32 s0, 0x2bc000
	s_nop 0
	v_addc_co_u32_e32 v3, vcc, 0, v19, vcc
	global_store_short v[2:3], v4, off
	v_add_co_u32_e32 v2, vcc, s0, v20
	s_nop 1
	v_addc_co_u32_e32 v3, vcc, 0, v21, vcc
	global_load_ushort v2, v[2:3], off
	v_mul_f32_e32 v3, v5, v1
	s_waitcnt vmcnt(0)
	v_lshlrev_b32_e32 v2, 16, v2
	v_mul_f32_e32 v2, v3, v2
	v_cvt_pk_bf16_f32 v4, v2, s0
	s_mov_b32 s0, 0xdb06000
	v_add_co_u32_e32 v2, vcc, s0, v18
	s_mov_b32 s0, 0x320000
	s_nop 0
	v_addc_co_u32_e32 v3, vcc, 0, v19, vcc
	global_store_short v[2:3], v4, off
	v_add_co_u32_e32 v2, vcc, s0, v20
	s_nop 1
	v_addc_co_u32_e32 v3, vcc, 0, v21, vcc
	global_load_ushort v2, v[2:3], off
	v_mul_f32_e32 v3, v6, v1
	s_waitcnt vmcnt(0)
	v_lshlrev_b32_e32 v2, 16, v2
	v_mul_f32_e32 v2, v3, v2
	v_cvt_pk_bf16_f32 v4, v2, s0
	s_mov_b32 s0, 0xdb6a000
	v_add_co_u32_e32 v2, vcc, s0, v18
	s_mov_b32 s0, 0x334000
	s_nop 0
	v_addc_co_u32_e32 v3, vcc, 0, v19, vcc
	global_store_short v[2:3], v4, off
	v_add_co_u32_e32 v2, vcc, s0, v20
	s_nop 1
	v_addc_co_u32_e32 v3, vcc, 0, v21, vcc
	global_load_ushort v2, v[2:3], off
	v_mul_f32_e32 v3, v7, v1
	s_waitcnt vmcnt(0)
	v_lshlrev_b32_e32 v2, 16, v2
	v_mul_f32_e32 v2, v3, v2
	v_cvt_pk_bf16_f32 v4, v2, s0
	s_mov_b32 s0, 0xdb7e000
	v_add_co_u32_e32 v2, vcc, s0, v18
	s_mov_b32 s0, 0x348000
	s_nop 0
	v_addc_co_u32_e32 v3, vcc, 0, v19, vcc
	global_store_short v[2:3], v4, off
	v_add_co_u32_e32 v2, vcc, s0, v20
	s_nop 1
	v_addc_co_u32_e32 v3, vcc, 0, v21, vcc
	global_load_ushort v2, v[2:3], off
	v_mul_f32_e32 v3, v8, v1
	s_waitcnt vmcnt(0)
	v_lshlrev_b32_e32 v2, 16, v2
	v_mul_f32_e32 v2, v3, v2
	v_cvt_pk_bf16_f32 v4, v2, s0
	s_mov_b32 s0, 0xdb92000
	v_add_co_u32_e32 v2, vcc, s0, v18
	s_mov_b32 s0, 0x35c000
	s_nop 0
	v_addc_co_u32_e32 v3, vcc, 0, v19, vcc
	global_store_short v[2:3], v4, off
	v_add_co_u32_e32 v2, vcc, s0, v20
	s_nop 1
	v_addc_co_u32_e32 v3, vcc, 0, v21, vcc
	global_load_ushort v2, v[2:3], off
	v_mul_f32_e32 v3, v9, v1
	s_waitcnt vmcnt(0)
	v_lshlrev_b32_e32 v2, 16, v2
	v_mul_f32_e32 v2, v3, v2
	v_cvt_pk_bf16_f32 v4, v2, s0
	s_mov_b32 s0, 0xdba6000
	v_add_co_u32_e32 v2, vcc, s0, v18
	s_mov_b32 s0, 0x3c0000
	s_nop 0
	v_addc_co_u32_e32 v3, vcc, 0, v19, vcc
	global_store_short v[2:3], v4, off
	v_add_co_u32_e32 v2, vcc, s0, v20
	s_nop 1
	v_addc_co_u32_e32 v3, vcc, 0, v21, vcc
	global_load_ushort v2, v[2:3], off
	v_mul_f32_e32 v3, v10, v1
	s_waitcnt vmcnt(0)
	v_lshlrev_b32_e32 v2, 16, v2
	v_mul_f32_e32 v2, v3, v2
	v_cvt_pk_bf16_f32 v4, v2, s0
	s_mov_b32 s0, 0xdc0a000
	v_add_co_u32_e32 v2, vcc, s0, v18
	s_mov_b32 s0, 0x3d4000
	s_nop 0
	v_addc_co_u32_e32 v3, vcc, 0, v19, vcc
	global_store_short v[2:3], v4, off
	v_add_co_u32_e32 v2, vcc, s0, v20
	s_nop 1
	v_addc_co_u32_e32 v3, vcc, 0, v21, vcc
	global_load_ushort v2, v[2:3], off
	v_mul_f32_e32 v3, v11, v1
	s_waitcnt vmcnt(0)
	v_lshlrev_b32_e32 v2, 16, v2
	v_mul_f32_e32 v2, v3, v2
	v_cvt_pk_bf16_f32 v4, v2, s0
	s_mov_b32 s0, 0xdc1e000
	v_add_co_u32_e32 v2, vcc, s0, v18
	s_mov_b32 s0, 0x3e8000
	s_nop 0
	v_addc_co_u32_e32 v3, vcc, 0, v19, vcc
	global_store_short v[2:3], v4, off
	v_add_co_u32_e32 v2, vcc, s0, v20
	s_nop 1
	v_addc_co_u32_e32 v3, vcc, 0, v21, vcc
	global_load_ushort v2, v[2:3], off
	v_mul_f32_e32 v3, v12, v1
	s_waitcnt vmcnt(0)
	v_lshlrev_b32_e32 v2, 16, v2
	v_mul_f32_e32 v2, v3, v2
	v_cvt_pk_bf16_f32 v4, v2, s0
	s_mov_b32 s0, 0xdc32000
	v_add_co_u32_e32 v2, vcc, s0, v18
	s_mov_b32 s0, 0x3fc000
	s_nop 0
	v_addc_co_u32_e32 v3, vcc, 0, v19, vcc
	global_store_short v[2:3], v4, off
	v_add_co_u32_e32 v2, vcc, s0, v20
	s_nop 1
	v_addc_co_u32_e32 v3, vcc, 0, v21, vcc
	global_load_ushort v2, v[2:3], off
	v_mul_f32_e32 v3, v13, v1
	s_waitcnt vmcnt(0)
	v_lshlrev_b32_e32 v2, 16, v2
	v_mul_f32_e32 v2, v3, v2
	v_cvt_pk_bf16_f32 v4, v2, s0
	s_mov_b32 s0, 0xdc46000
	v_add_co_u32_e32 v2, vcc, s0, v18
	s_mov_b32 s0, 0x460000
	s_nop 0
	v_addc_co_u32_e32 v3, vcc, 0, v19, vcc
	global_store_short v[2:3], v4, off
	v_add_co_u32_e32 v2, vcc, s0, v20
	s_nop 1
	v_addc_co_u32_e32 v3, vcc, 0, v21, vcc
	global_load_ushort v2, v[2:3], off
	v_mul_f32_e32 v3, v14, v1
	s_waitcnt vmcnt(0)
	v_lshlrev_b32_e32 v2, 16, v2
	v_mul_f32_e32 v2, v3, v2
	v_cvt_pk_bf16_f32 v4, v2, s0
	s_mov_b32 s0, 0xdcaa000
	v_add_co_u32_e32 v2, vcc, s0, v18
	s_mov_b32 s0, 0x474000
	s_nop 0
	v_addc_co_u32_e32 v3, vcc, 0, v19, vcc
	global_store_short v[2:3], v4, off
	v_add_co_u32_e32 v2, vcc, s0, v20
	s_nop 1
	v_addc_co_u32_e32 v3, vcc, 0, v21, vcc
	global_load_ushort v2, v[2:3], off
	v_mul_f32_e32 v3, v15, v1
	s_waitcnt vmcnt(0)
	v_lshlrev_b32_e32 v2, 16, v2
	v_mul_f32_e32 v2, v3, v2
	v_cvt_pk_bf16_f32 v4, v2, s0
	s_mov_b32 s0, 0xdcbe000
	v_add_co_u32_e32 v2, vcc, s0, v18
	s_mov_b32 s0, 0x488000
	s_nop 0
	v_addc_co_u32_e32 v3, vcc, 0, v19, vcc
	global_store_short v[2:3], v4, off
	v_add_co_u32_e32 v2, vcc, s0, v20
	s_nop 1
	v_addc_co_u32_e32 v3, vcc, 0, v21, vcc
	global_load_ushort v2, v[2:3], off
	v_mul_f32_e32 v3, v16, v1
	v_mul_f32_e32 v1, v17, v1
	s_waitcnt vmcnt(0)
	v_lshlrev_b32_e32 v2, 16, v2
	v_mul_f32_e32 v2, v3, v2
	v_cvt_pk_bf16_f32 v4, v2, s0
	s_mov_b32 s0, 0xdcd2000
	v_add_co_u32_e32 v2, vcc, s0, v18
	s_nop 1
	v_addc_co_u32_e32 v3, vcc, 0, v19, vcc
	global_store_short v[2:3], v4, off
	v_add_co_u32_e32 v2, vcc, 0x49c000, v20
	s_nop 1
	v_addc_co_u32_e32 v3, vcc, 0, v21, vcc
	global_load_ushort v2, v[2:3], off
	s_waitcnt vmcnt(0)
	v_lshlrev_b32_e32 v2, 16, v2
	v_mul_f32_e32 v1, v1, v2
	v_add_co_u32_e32 v2, vcc, 0xdce6000, v18
	v_cvt_pk_bf16_f32 v1, v1, s0
	s_nop 0
	v_addc_co_u32_e32 v3, vcc, 0, v19, vcc
	global_store_short v[2:3], v1, off

.LBB0_657:
	s_and_b64 vcc, exec, s[0:1]
	s_cbranch_vccz .LBB0_806
	s_add_i32 s0, s46, 0xfffff600
	s_mul_i32 s1, s0, 0xfc1
	s_lshr_b32 s1, s1, 20
	s_mul_i32 s2, s1, 0xfffffefc
	s_add_i32 s0, s2, s0
	s_mul_i32 s2, s0, 0xfc1
	s_lshr_b32 s22, s2, 31
	s_ashr_i32 s2, s2, 18
	s_add_i32 s2, s2, s22
	s_mul_i32 s24, s2, 0xffffffbf
	s_add_i32 s24, s24, s0
	s_lshl_b32 s0, s1, 12
	s_add_i32 s28, s0, 0x2000
	s_and_b32 s35, s24, 0xffffffbf
	s_cmp_lg_u32 s35, 0
	s_cselect_b64 s[22:23], -1, 0
	s_lshl_b32 s34, s2, 7
	s_add_i32 s0, s24, s34
	s_mul_hi_i32 s1, s0, 0xa000
	s_mul_i32 s0, s0, 0xa000
	s_lshl_b64 s[0:1], s[0:1], 1
	v_readlane_b32 s4, v246, 4
	v_readlane_b32 s5, v246, 5
	s_add_u32 s29, s4, s0
	s_addc_u32 s36, s5, s1
	s_lshl_b32 s2, s28, 1
	v_mov_b32_e32 v2, v184
	s_add_u32 s28, s29, s2
	s_addc_u32 s29, s36, 0
	v_ashrrev_i32_e32 v3, 31, v2
	v_lshl_add_u64 v[18:19], v[2:3], 1, s[28:29]
	global_load_ushort v1, v[18:19], off
	s_cmp_eq_u32 s35, 0
	s_cselect_b64 s[28:29], -1, 0
	s_and_b64 vcc, s[28:29], exec
	s_cselect_b32 s28, 1, s24
	s_add_i32 s28, s28, s34
	s_add_i32 s28, s28, 64
	s_mul_hi_i32 s29, s28, 0x14000
	s_mul_i32 s28, s28, 0x14000
	s_add_u32 s28, s4, s28
	s_addc_u32 s29, s5, s29
	s_add_u32 s28, s28, s2
	s_addc_u32 s29, s29, 0
	v_mov_b32_e32 v9, 0
	v_lshl_add_u64 v[20:21], v[2:3], 1, s[28:29]
	s_mov_b32 s100, 0x1000
	s_mov_b32 s101, 0
	v_lshl_add_u64 v[250:251], v[18:19], 0, s[100:101]
	v_lshl_add_u64 v[252:253], v[20:21], 0, s[100:101]
	global_load_ushort v255, v[18:19], off offset:512
	global_load_ushort v255, v[18:19], off offset:1024
	global_load_ushort v255, v[18:19], off offset:1536
	global_load_ushort v255, v[18:19], off offset:2048
	global_load_ushort v255, v[18:19], off offset:2560
	global_load_ushort v255, v[18:19], off offset:3072
	global_load_ushort v255, v[18:19], off offset:3584
	global_load_ushort v255, v[250:251], off
	global_load_ushort v255, v[250:251], off offset:512
	global_load_ushort v255, v[250:251], off offset:1024
	global_load_ushort v255, v[250:251], off offset:1536
	global_load_ushort v255, v[250:251], off offset:2048
	global_load_ushort v255, v[250:251], off offset:2560
	global_load_ushort v255, v[250:251], off offset:3072
	global_load_ushort v255, v[250:251], off offset:3584
	global_load_ushort v255, v[20:21], off
	global_load_ushort v255, v[20:21], off offset:512
	global_load_ushort v255, v[20:21], off offset:1024
	global_load_ushort v255, v[20:21], off offset:1536
	global_load_ushort v255, v[20:21], off offset:2048
	global_load_ushort v255, v[20:21], off offset:2560
	global_load_ushort v255, v[20:21], off offset:3072
	global_load_ushort v255, v[20:21], off offset:3584
	global_load_ushort v255, v[252:253], off
	global_load_ushort v255, v[252:253], off offset:512
	global_load_ushort v255, v[252:253], off offset:1024
	global_load_ushort v255, v[252:253], off offset:1536
	global_load_ushort v255, v[252:253], off offset:2048
	global_load_ushort v255, v[252:253], off offset:2560
	global_load_ushort v255, v[252:253], off offset:3072
	global_load_ushort v255, v[252:253], off offset:3584
	v_mov_b32_e32 v13, 0
	s_cbranch_vccnz .LBB0_660
	global_load_ushort v3, v[20:21], off
	s_waitcnt vmcnt(0)
	v_lshlrev_b32_e32 v13, 16, v3

.LBB0_704:
	v_readlane_b32 s0, v246, 36
	v_lshlrev_b64 v[34:35], 1, v[82:83]
	v_readlane_b32 s1, v246, 37
	v_lshl_or_b32 v38, v98, 2, s2
	v_mul_u32_u24_e32 v38, 0x14000, v38
	v_lshl_add_u64 v[36:37], s[0:1], 0, v[34:35]
	v_mov_b32_e32 v39, v0
	v_lshl_add_u64 v[36:37], v[36:37], 0, v[38:39]
	s_mov_b32 s101, 0
	s_mov_b32 s100, 0x14000
	v_lshl_add_u64 v[250:251], v[36:37], 0, s[100:101]
	global_load_ushort v255, v[250:251], off
	s_mov_b32 s100, 0x28000
	v_lshl_add_u64 v[252:253], v[36:37], 0, s[100:101]
	global_load_ushort v255, v[252:253], off
	s_mov_b32 s100, 0x3c000
	v_lshl_add_u64 v[250:251], v[36:37], 0, s[100:101]
	global_load_ushort v255, v[250:251], off
	s_mov_b32 s100, 0xa0000
	v_lshl_add_u64 v[252:253], v[36:37], 0, s[100:101]
	global_load_ushort v255, v[252:253], off
	s_mov_b32 s100, 0xb4000
	v_lshl_add_u64 v[250:251], v[36:37], 0, s[100:101]
	global_load_ushort v255, v[250:251], off
	s_mov_b32 s100, 0xc8000
	v_lshl_add_u64 v[252:253], v[36:37], 0, s[100:101]
	global_load_ushort v255, v[252:253], off
	s_mov_b32 s100, 0xdc000
	v_lshl_add_u64 v[250:251], v[36:37], 0, s[100:101]
	global_load_ushort v255, v[250:251], off
	s_mov_b32 s100, 0x140000
	v_lshl_add_u64 v[252:253], v[36:37], 0, s[100:101]
	global_load_ushort v255, v[252:253], off
	s_mov_b32 s100, 0x154000
	v_lshl_add_u64 v[250:251], v[36:37], 0, s[100:101]
	global_load_ushort v255, v[250:251], off
	s_mov_b32 s100, 0x168000
	v_lshl_add_u64 v[252:253], v[36:37], 0, s[100:101]
	global_load_ushort v255, v[252:253], off
	s_mov_b32 s100, 0x17c000
	v_lshl_add_u64 v[250:251], v[36:37], 0, s[100:101]
	global_load_ushort v255, v[250:251], off
	s_mov_b32 s100, 0x1e0000
	v_lshl_add_u64 v[252:253], v[36:37], 0, s[100:101]
	global_load_ushort v255, v[252:253], off
	s_mov_b32 s100, 0x1f4000
	v_lshl_add_u64 v[250:251], v[36:37], 0, s[100:101]
	global_load_ushort v255, v[250:251], off
	s_mov_b32 s100, 0x208000
	v_lshl_add_u64 v[252:253], v[36:37], 0, s[100:101]
	global_load_ushort v255, v[252:253], off
	s_mov_b32 s100, 0x21c000
	v_lshl_add_u64 v[250:251], v[36:37], 0, s[100:101]
	global_load_ushort v255, v[250:251], off
	s_mov_b32 s100, 0x280000
	v_lshl_add_u64 v[252:253], v[36:37], 0, s[100:101]
	global_load_ushort v255, v[252:253], off
	s_mov_b32 s100, 0x294000
	v_lshl_add_u64 v[250:251], v[36:37], 0, s[100:101]
	global_load_ushort v255, v[250:251], off
	s_mov_b32 s100, 0x2a8000
	v_lshl_add_u64 v[252:253], v[36:37], 0, s[100:101]
	global_load_ushort v255, v[252:253], off
	s_mov_b32 s100, 0x2bc000
	v_lshl_add_u64 v[250:251], v[36:37], 0, s[100:101]
	global_load_ushort v255, v[250:251], off
	s_mov_b32 s100, 0x320000
	v_lshl_add_u64 v[252:253], v[36:37], 0, s[100:101]
	global_load_ushort v255, v[252:253], off
	s_mov_b32 s100, 0x334000
	v_lshl_add_u64 v[250:251], v[36:37], 0, s[100:101]
	global_load_ushort v255, v[250:251], off
	s_mov_b32 s100, 0x348000
	v_lshl_add_u64 v[252:253], v[36:37], 0, s[100:101]
	global_load_ushort v255, v[252:253], off
	s_mov_b32 s100, 0x35c000
	v_lshl_add_u64 v[250:251], v[36:37], 0, s[100:101]
	global_load_ushort v255, v[250:251], off
	s_mov_b32 s100, 0x3c0000
	v_lshl_add_u64 v[252:253], v[36:37], 0, s[100:101]
	global_load_ushort v255, v[252:253], off
	s_mov_b32 s100, 0x3d4000
	v_lshl_add_u64 v[250:251], v[36:37], 0, s[100:101]
	global_load_ushort v255, v[250:251], off
	s_mov_b32 s100, 0x3e8000
	v_lshl_add_u64 v[252:253], v[36:37], 0, s[100:101]
	global_load_ushort v255, v[252:253], off
	s_mov_b32 s100, 0x3fc000
	v_lshl_add_u64 v[250:251], v[36:37], 0, s[100:101]
	global_load_ushort v255, v[250:251], off
	s_mov_b32 s100, 0x460000
	v_lshl_add_u64 v[252:253], v[36:37], 0, s[100:101]
	global_load_ushort v255, v[252:253], off
	s_mov_b32 s100, 0x474000
	v_lshl_add_u64 v[250:251], v[36:37], 0, s[100:101]
	global_load_ushort v255, v[250:251], off
	s_mov_b32 s100, 0x488000
	v_lshl_add_u64 v[252:253], v[36:37], 0, s[100:101]
	global_load_ushort v255, v[252:253], off
	s_mov_b32 s100, 0x49c000
	v_lshl_add_u64 v[250:251], v[36:37], 0, s[100:101]
	global_load_ushort v255, v[250:251], off
	global_load_ushort v40, v[36:37], off
	ds_bpermute_b32 v1, v87, v103
	v_lshl_add_u64 v[38:39], s[68:69], 0, v[38:39]
	v_lshl_add_u64 v[34:35], v[38:39], 0, v[34:35]
	s_waitcnt lgkmcnt(0)
	v_add_f32_e32 v1, v103, v1
	v_rcp_f32_e32 v1, v1
	s_waitcnt vmcnt(0)
	v_lshlrev_b32_e32 v40, 16, v40
	v_mul_f32_e32 v18, v18, v1
	v_mul_f32_e32 v18, v18, v40
	v_cvt_pk_bf16_f32 v18, v18, s0
	s_mov_b32 s0, 0xd84a000
	v_add_co_u32_e32 v38, vcc, s0, v34
	v_mul_f32_e32 v19, v19, v1
	s_nop 0
	v_addc_co_u32_e32 v39, vcc, 0, v35, vcc
	global_store_short v[38:39], v18, off
	v_add_co_u32_e32 v38, vcc, s97, v36
	v_mul_f32_e32 v2, v2, v1
	s_nop 0
	v_addc_co_u32_e32 v39, vcc, 0, v37, vcc
	global_load_ushort v18, v[38:39], off
	v_mul_f32_e32 v3, v3, v1
	s_waitcnt vmcnt(0)
	v_lshlrev_b32_e32 v18, 16, v18
	v_mul_f32_e32 v18, v19, v18
	v_cvt_pk_bf16_f32 v38, v18, s0
	s_mov_b32 s0, 0xd85e000
	v_add_co_u32_e32 v18, vcc, s0, v34
	s_mov_b32 s0, 0x28000
	s_nop 0
	v_addc_co_u32_e32 v19, vcc, 0, v35, vcc
	global_store_short v[18:19], v38, off
	v_add_co_u32_e32 v18, vcc, s0, v36
	s_nop 1
	v_addc_co_u32_e32 v19, vcc, 0, v37, vcc
	global_load_ushort v18, v[18:19], off
	v_mul_f32_e32 v19, v20, v1
	s_waitcnt vmcnt(0)
	v_lshlrev_b32_e32 v18, 16, v18
	v_mul_f32_e32 v18, v19, v18
	v_cvt_pk_bf16_f32 v20, v18, s0
	s_mov_b32 s0, 0xd872000
	v_add_co_u32_e32 v18, vcc, s0, v34
	s_mov_b32 s0, 0x3c000
	s_nop 0
	v_addc_co_u32_e32 v19, vcc, 0, v35, vcc
	global_store_short v[18:19], v20, off
	v_add_co_u32_e32 v18, vcc, s0, v36
	s_nop 1
	v_addc_co_u32_e32 v19, vcc, 0, v37, vcc
	global_load_ushort v18, v[18:19], off
	v_mul_f32_e32 v19, v21, v1
	s_waitcnt vmcnt(0)
	v_lshlrev_b32_e32 v18, 16, v18
	v_mul_f32_e32 v18, v19, v18
	v_cvt_pk_bf16_f32 v20, v18, s0
	s_mov_b32 s0, 0xd886000
	v_add_co_u32_e32 v18, vcc, s0, v34
	s_mov_b32 s0, 0xa0000
	s_nop 0
	v_addc_co_u32_e32 v19, vcc, 0, v35, vcc
	global_store_short v[18:19], v20, off
	v_add_co_u32_e32 v18, vcc, s0, v36
	s_nop 1
	v_addc_co_u32_e32 v19, vcc, 0, v37, vcc
	global_load_ushort v18, v[18:19], off
	v_mul_f32_e32 v19, v22, v1
	s_waitcnt vmcnt(0)
	v_lshlrev_b32_e32 v18, 16, v18
	v_mul_f32_e32 v18, v19, v18
	v_cvt_pk_bf16_f32 v20, v18, s0
	s_mov_b32 s0, 0xd8ea000
	v_add_co_u32_e32 v18, vcc, s0, v34
	s_mov_b32 s0, 0xb4000
	s_nop 0
	v_addc_co_u32_e32 v19, vcc, 0, v35, vcc
	global_store_short v[18:19], v20, off
	v_add_co_u32_e32 v18, vcc, s0, v36
	s_nop 1
	v_addc_co_u32_e32 v19, vcc, 0, v37, vcc
	global_load_ushort v18, v[18:19], off
	v_mul_f32_e32 v19, v23, v1
	s_waitcnt vmcnt(0)
	v_lshlrev_b32_e32 v18, 16, v18
	v_mul_f32_e32 v18, v19, v18
	v_cvt_pk_bf16_f32 v20, v18, s0
	s_mov_b32 s0, 0xd8fe000
	v_add_co_u32_e32 v18, vcc, s0, v34
	s_mov_b32 s0, 0xc8000
	s_nop 0
	v_addc_co_u32_e32 v19, vcc, 0, v35, vcc
	global_store_short v[18:19], v20, off
	v_add_co_u32_e32 v18, vcc, s0, v36
	s_nop 1
	v_addc_co_u32_e32 v19, vcc, 0, v37, vcc
	global_load_ushort v18, v[18:19], off
	v_mul_f32_e32 v19, v24, v1
	s_waitcnt vmcnt(0)
	v_lshlrev_b32_e32 v18, 16, v18
	v_mul_f32_e32 v18, v19, v18
	v_cvt_pk_bf16_f32 v20, v18, s0
	s_mov_b32 s0, 0xd912000
	v_add_co_u32_e32 v18, vcc, s0, v34
	s_mov_b32 s0, 0xdc000
	s_nop 0
	v_addc_co_u32_e32 v19, vcc, 0, v35, vcc
	global_store_short v[18:19], v20, off
	v_add_co_u32_e32 v18, vcc, s0, v36
	s_nop 1
	v_addc_co_u32_e32 v19, vcc, 0, v37, vcc
	global_load_ushort v18, v[18:19], off
	v_mul_f32_e32 v19, v25, v1
	s_waitcnt vmcnt(0)
	v_lshlrev_b32_e32 v18, 16, v18
	v_mul_f32_e32 v18, v19, v18
	v_cvt_pk_bf16_f32 v20, v18, s0
	s_mov_b32 s0, 0xd926000
	v_add_co_u32_e32 v18, vcc, s0, v34
	s_mov_b32 s0, 0x140000
	s_nop 0
	v_addc_co_u32_e32 v19, vcc, 0, v35, vcc
	global_store_short v[18:19], v20, off
	v_add_co_u32_e32 v18, vcc, s0, v36
	s_nop 1
	v_addc_co_u32_e32 v19, vcc, 0, v37, vcc
	global_load_ushort v18, v[18:19], off
	v_mul_f32_e32 v19, v26, v1
	s_waitcnt vmcnt(0)
	v_lshlrev_b32_e32 v18, 16, v18
	v_mul_f32_e32 v18, v19, v18
	v_cvt_pk_bf16_f32 v20, v18, s0
	s_mov_b32 s0, 0xd98a000
	v_add_co_u32_e32 v18, vcc, s0, v34
	s_mov_b32 s0, 0x154000
	s_nop 0
	v_addc_co_u32_e32 v19, vcc, 0, v35, vcc
	global_store_short v[18:19], v20, off
	v_add_co_u32_e32 v18, vcc, s0, v36
	s_nop 1
	v_addc_co_u32_e32 v19, vcc, 0, v37, vcc
	global_load_ushort v18, v[18:19], off
	v_mul_f32_e32 v19, v27, v1
	s_waitcnt vmcnt(0)
	v_lshlrev_b32_e32 v18, 16, v18
	v_mul_f32_e32 v18, v19, v18
	v_cvt_pk_bf16_f32 v20, v18, s0
	s_mov_b32 s0, 0xd99e000
	v_add_co_u32_e32 v18, vcc, s0, v34
	s_mov_b32 s0, 0x168000
	s_nop 0
	v_addc_co_u32_e32 v19, vcc, 0, v35, vcc
	global_store_short v[18:19], v20, off
	v_add_co_u32_e32 v18, vcc, s0, v36
	s_nop 1
	v_addc_co_u32_e32 v19, vcc, 0, v37, vcc
	global_load_ushort v18, v[18:19], off
	v_mul_f32_e32 v19, v28, v1
	s_waitcnt vmcnt(0)
	v_lshlrev_b32_e32 v18, 16, v18
	v_mul_f32_e32 v18, v19, v18
	v_cvt_pk_bf16_f32 v20, v18, s0
	s_mov_b32 s0, 0xd9b2000
	v_add_co_u32_e32 v18, vcc, s0, v34
	s_mov_b32 s0, 0x17c000
	s_nop 0
	v_addc_co_u32_e32 v19, vcc, 0, v35, vcc
	global_store_short v[18:19], v20, off
	v_add_co_u32_e32 v18, vcc, s0, v36
	s_nop 1
	v_addc_co_u32_e32 v19, vcc, 0, v37, vcc
	global_load_ushort v18, v[18:19], off
	v_mul_f32_e32 v19, v29, v1
	s_waitcnt vmcnt(0)
	v_lshlrev_b32_e32 v18, 16, v18
	v_mul_f32_e32 v18, v19, v18
	v_cvt_pk_bf16_f32 v20, v18, s0
	s_mov_b32 s0, 0xd9c6000
	v_add_co_u32_e32 v18, vcc, s0, v34
	s_mov_b32 s0, 0x1e0000
	s_nop 0
	v_addc_co_u32_e32 v19, vcc, 0, v35, vcc
	global_store_short v[18:19], v20, off
	v_add_co_u32_e32 v18, vcc, s0, v36
	s_nop 1
	v_addc_co_u32_e32 v19, vcc, 0, v37, vcc
	global_load_ushort v18, v[18:19], off
	v_mul_f32_e32 v19, v30, v1
	s_waitcnt vmcnt(0)
	v_lshlrev_b32_e32 v18, 16, v18
	v_mul_f32_e32 v18, v19, v18
	v_cvt_pk_bf16_f32 v20, v18, s0
	s_mov_b32 s0, 0xda2a000
	v_add_co_u32_e32 v18, vcc, s0, v34
	s_mov_b32 s0, 0x1f4000
	s_nop 0
	v_addc_co_u32_e32 v19, vcc, 0, v35, vcc
	global_store_short v[18:19], v20, off
	v_add_co_u32_e32 v18, vcc, s0, v36
	s_nop 1
	v_addc_co_u32_e32 v19, vcc, 0, v37, vcc
	global_load_ushort v18, v[18:19], off
	v_mul_f32_e32 v19, v31, v1
	s_waitcnt vmcnt(0)
	v_lshlrev_b32_e32 v18, 16, v18
	v_mul_f32_e32 v18, v19, v18
	v_cvt_pk_bf16_f32 v20, v18, s0
	s_mov_b32 s0, 0xda3e000
	v_add_co_u32_e32 v18, vcc, s0, v34
	s_mov_b32 s0, 0x208000
	s_nop 0
	v_addc_co_u32_e32 v19, vcc, 0, v35, vcc
	global_store_short v[18:19], v20, off
	v_add_co_u32_e32 v18, vcc, s0, v36
	s_nop 1
	v_addc_co_u32_e32 v19, vcc, 0, v37, vcc
	global_load_ushort v18, v[18:19], off
	v_mul_f32_e32 v19, v32, v1
	s_waitcnt vmcnt(0)
	v_lshlrev_b32_e32 v18, 16, v18
	v_mul_f32_e32 v18, v19, v18
	v_cvt_pk_bf16_f32 v20, v18, s0
	s_mov_b32 s0, 0xda52000
	v_add_co_u32_e32 v18, vcc, s0, v34
	s_mov_b32 s0, 0x21c000
	s_nop 0
	v_addc_co_u32_e32 v19, vcc, 0, v35, vcc
	global_store_short v[18:19], v20, off
	v_add_co_u32_e32 v18, vcc, s0, v36
	s_nop 1
	v_addc_co_u32_e32 v19, vcc, 0, v37, vcc
	global_load_ushort v18, v[18:19], off
	v_mul_f32_e32 v19, v33, v1
	s_waitcnt vmcnt(0)
	v_lshlrev_b32_e32 v18, 16, v18
	v_mul_f32_e32 v18, v19, v18
	v_cvt_pk_bf16_f32 v20, v18, s0
	s_mov_b32 s0, 0xda66000
	v_add_co_u32_e32 v18, vcc, s0, v34
	s_mov_b32 s0, 0x280000
	s_nop 0
	v_addc_co_u32_e32 v19, vcc, 0, v35, vcc
	global_store_short v[18:19], v20, off
	v_add_co_u32_e32 v18, vcc, s0, v36
	s_nop 1
	v_addc_co_u32_e32 v19, vcc, 0, v37, vcc
	global_load_ushort v18, v[18:19], off
	s_waitcnt vmcnt(0)
	v_lshlrev_b32_e32 v18, 16, v18
	v_mul_f32_e32 v2, v2, v18
	v_cvt_pk_bf16_f32 v2, v2, s0
	s_mov_b32 s0, 0xdaca000
	v_add_co_u32_e32 v18, vcc, s0, v34
	s_mov_b32 s0, 0x294000
	s_nop 0
	v_addc_co_u32_e32 v19, vcc, 0, v35, vcc
	global_store_short v[18:19], v2, off
	v_add_co_u32_e32 v18, vcc, s0, v36
	s_nop 1
	v_addc_co_u32_e32 v19, vcc, 0, v37, vcc
	global_load_ushort v2, v[18:19], off
	s_waitcnt vmcnt(0)
	v_lshlrev_b32_e32 v2, 16, v2
	v_mul_f32_e32 v2, v3, v2
	v_cvt_pk_bf16_f32 v18, v2, s0
	s_mov_b32 s0, 0xdade000
	v_add_co_u32_e32 v2, vcc, s0, v34
	s_mov_b32 s0, 0x2a8000
	s_nop 0
	v_addc_co_u32_e32 v3, vcc, 0, v35, vcc
	global_store_short v[2:3], v18, off
	v_add_co_u32_e32 v2, vcc, s0, v36
	s_nop 1
	v_addc_co_u32_e32 v3, vcc, 0, v37, vcc
	global_load_ushort v2, v[2:3], off
	v_mul_f32_e32 v3, v4, v1
	s_waitcnt vmcnt(0)
	v_lshlrev_b32_e32 v2, 16, v2
	v_mul_f32_e32 v2, v3, v2
	v_cvt_pk_bf16_f32 v4, v2, s0
	s_mov_b32 s0, 0xdaf2000
	v_add_co_u32_e32 v2, vcc, s0, v34
	s_mov_b32 s0, 0x2bc000
	s_nop 0
	v_addc_co_u32_e32 v3, vcc, 0, v35, vcc
	global_store_short v[2:3], v4, off
	v_add_co_u32_e32 v2, vcc, s0, v36
	s_nop 1
	v_addc_co_u32_e32 v3, vcc, 0, v37, vcc
	global_load_ushort v2, v[2:3], off
	v_mul_f32_e32 v3, v5, v1
	s_waitcnt vmcnt(0)
	v_lshlrev_b32_e32 v2, 16, v2
	v_mul_f32_e32 v2, v3, v2
	v_cvt_pk_bf16_f32 v4, v2, s0
	s_mov_b32 s0, 0xdb06000
	v_add_co_u32_e32 v2, vcc, s0, v34
	s_mov_b32 s0, 0x320000
	s_nop 0
	v_addc_co_u32_e32 v3, vcc, 0, v35, vcc
	global_store_short v[2:3], v4, off
	v_add_co_u32_e32 v2, vcc, s0, v36
	s_nop 1
	v_addc_co_u32_e32 v3, vcc, 0, v37, vcc
	global_load_ushort v2, v[2:3], off
	v_mul_f32_e32 v3, v6, v1
	s_waitcnt vmcnt(0)
	v_lshlrev_b32_e32 v2, 16, v2
	v_mul_f32_e32 v2, v3, v2
	v_cvt_pk_bf16_f32 v4, v2, s0
	s_mov_b32 s0, 0xdb6a000
	v_add_co_u32_e32 v2, vcc, s0, v34
	s_mov_b32 s0, 0x334000
	s_nop 0
	v_addc_co_u32_e32 v3, vcc, 0, v35, vcc
	global_store_short v[2:3], v4, off
	v_add_co_u32_e32 v2, vcc, s0, v36
	s_nop 1
	v_addc_co_u32_e32 v3, vcc, 0, v37, vcc
	global_load_ushort v2, v[2:3], off
	v_mul_f32_e32 v3, v7, v1
	s_waitcnt vmcnt(0)
	v_lshlrev_b32_e32 v2, 16, v2
	v_mul_f32_e32 v2, v3, v2
	v_cvt_pk_bf16_f32 v4, v2, s0
	s_mov_b32 s0, 0xdb7e000
	v_add_co_u32_e32 v2, vcc, s0, v34
	s_mov_b32 s0, 0x348000
	s_nop 0
	v_addc_co_u32_e32 v3, vcc, 0, v35, vcc
	global_store_short v[2:3], v4, off
	v_add_co_u32_e32 v2, vcc, s0, v36
	s_nop 1
	v_addc_co_u32_e32 v3, vcc, 0, v37, vcc
	global_load_ushort v2, v[2:3], off
	v_mul_f32_e32 v3, v8, v1
	s_waitcnt vmcnt(0)
	v_lshlrev_b32_e32 v2, 16, v2
	v_mul_f32_e32 v2, v3, v2
	v_cvt_pk_bf16_f32 v4, v2, s0
	s_mov_b32 s0, 0xdb92000
	v_add_co_u32_e32 v2, vcc, s0, v34
	s_mov_b32 s0, 0x35c000
	s_nop 0
	v_addc_co_u32_e32 v3, vcc, 0, v35, vcc
	global_store_short v[2:3], v4, off
	v_add_co_u32_e32 v2, vcc, s0, v36
	s_nop 1
	v_addc_co_u32_e32 v3, vcc, 0, v37, vcc
	global_load_ushort v2, v[2:3], off
	v_mul_f32_e32 v3, v9, v1
	s_waitcnt vmcnt(0)
	v_lshlrev_b32_e32 v2, 16, v2
	v_mul_f32_e32 v2, v3, v2
	v_cvt_pk_bf16_f32 v4, v2, s0
	s_mov_b32 s0, 0xdba6000
	v_add_co_u32_e32 v2, vcc, s0, v34
	s_mov_b32 s0, 0x3c0000
	s_nop 0
	v_addc_co_u32_e32 v3, vcc, 0, v35, vcc
	global_store_short v[2:3], v4, off
	v_add_co_u32_e32 v2, vcc, s0, v36
	s_nop 1
	v_addc_co_u32_e32 v3, vcc, 0, v37, vcc
	global_load_ushort v2, v[2:3], off
	v_mul_f32_e32 v3, v10, v1
	s_waitcnt vmcnt(0)
	v_lshlrev_b32_e32 v2, 16, v2
	v_mul_f32_e32 v2, v3, v2
	v_cvt_pk_bf16_f32 v4, v2, s0
	s_mov_b32 s0, 0xdc0a000
	v_add_co_u32_e32 v2, vcc, s0, v34
	s_mov_b32 s0, 0x3d4000
	s_nop 0
	v_addc_co_u32_e32 v3, vcc, 0, v35, vcc
	global_store_short v[2:3], v4, off
	v_add_co_u32_e32 v2, vcc, s0, v36
	s_nop 1
	v_addc_co_u32_e32 v3, vcc, 0, v37, vcc
	global_load_ushort v2, v[2:3], off
	v_mul_f32_e32 v3, v11, v1
	s_waitcnt vmcnt(0)
	v_lshlrev_b32_e32 v2, 16, v2
	v_mul_f32_e32 v2, v3, v2
	v_cvt_pk_bf16_f32 v4, v2, s0
	s_mov_b32 s0, 0xdc1e000
	v_add_co_u32_e32 v2, vcc, s0, v34
	s_mov_b32 s0, 0x3e8000
	s_nop 0
	v_addc_co_u32_e32 v3, vcc, 0, v35, vcc
	global_store_short v[2:3], v4, off
	v_add_co_u32_e32 v2, vcc, s0, v36
	s_nop 1
	v_addc_co_u32_e32 v3, vcc, 0, v37, vcc
	global_load_ushort v2, v[2:3], off
	v_mul_f32_e32 v3, v12, v1
	s_waitcnt vmcnt(0)
	v_lshlrev_b32_e32 v2, 16, v2
	v_mul_f32_e32 v2, v3, v2
	v_cvt_pk_bf16_f32 v4, v2, s0
	s_mov_b32 s0, 0xdc32000
	v_add_co_u32_e32 v2, vcc, s0, v34
	s_mov_b32 s0, 0x3fc000
	s_nop 0
	v_addc_co_u32_e32 v3, vcc, 0, v35, vcc
	global_store_short v[2:3], v4, off
	v_add_co_u32_e32 v2, vcc, s0, v36
	s_nop 1
	v_addc_co_u32_e32 v3, vcc, 0, v37, vcc
	global_load_ushort v2, v[2:3], off
	v_mul_f32_e32 v3, v13, v1
	s_waitcnt vmcnt(0)
	v_lshlrev_b32_e32 v2, 16, v2
	v_mul_f32_e32 v2, v3, v2
	v_cvt_pk_bf16_f32 v4, v2, s0
	s_mov_b32 s0, 0xdc46000
	v_add_co_u32_e32 v2, vcc, s0, v34
	s_mov_b32 s0, 0x460000
	s_nop 0
	v_addc_co_u32_e32 v3, vcc, 0, v35, vcc
	global_store_short v[2:3], v4, off
	v_add_co_u32_e32 v2, vcc, s0, v36
	s_nop 1
	v_addc_co_u32_e32 v3, vcc, 0, v37, vcc
	global_load_ushort v2, v[2:3], off
	v_mul_f32_e32 v3, v14, v1
	s_waitcnt vmcnt(0)
	v_lshlrev_b32_e32 v2, 16, v2
	v_mul_f32_e32 v2, v3, v2
	v_cvt_pk_bf16_f32 v4, v2, s0
	s_mov_b32 s0, 0xdcaa000
	v_add_co_u32_e32 v2, vcc, s0, v34
	s_mov_b32 s0, 0x474000
	s_nop 0
	v_addc_co_u32_e32 v3, vcc, 0, v35, vcc
	global_store_short v[2:3], v4, off
	v_add_co_u32_e32 v2, vcc, s0, v36
	s_nop 1
	v_addc_co_u32_e32 v3, vcc, 0, v37, vcc
	global_load_ushort v2, v[2:3], off
	v_mul_f32_e32 v3, v15, v1
	s_waitcnt vmcnt(0)
	v_lshlrev_b32_e32 v2, 16, v2
	v_mul_f32_e32 v2, v3, v2
	v_cvt_pk_bf16_f32 v4, v2, s0
	s_mov_b32 s0, 0xdcbe000
	v_add_co_u32_e32 v2, vcc, s0, v34
	s_mov_b32 s0, 0x488000
	s_nop 0
	v_addc_co_u32_e32 v3, vcc, 0, v35, vcc
	global_store_short v[2:3], v4, off
	v_add_co_u32_e32 v2, vcc, s0, v36
	s_nop 1
	v_addc_co_u32_e32 v3, vcc, 0, v37, vcc
	global_load_ushort v2, v[2:3], off
	v_mul_f32_e32 v3, v16, v1
	v_mul_f32_e32 v1, v17, v1
	s_waitcnt vmcnt(0)
	v_lshlrev_b32_e32 v2, 16, v2
	v_mul_f32_e32 v2, v3, v2
	v_cvt_pk_bf16_f32 v4, v2, s0
	s_mov_b32 s0, 0xdcd2000
	v_add_co_u32_e32 v2, vcc, s0, v34
	s_nop 1
	v_addc_co_u32_e32 v3, vcc, 0, v35, vcc
	global_store_short v[2:3], v4, off
	v_add_co_u32_e32 v2, vcc, 0x49c000, v36
	s_nop 1
	v_addc_co_u32_e32 v3, vcc, 0, v37, vcc
	global_load_ushort v2, v[2:3], off
	s_waitcnt vmcnt(0)
	v_lshlrev_b32_e32 v2, 16, v2
	v_mul_f32_e32 v1, v1, v2
	v_add_co_u32_e32 v2, vcc, 0xdce6000, v34
	v_cvt_pk_bf16_f32 v1, v1, s0
	s_nop 0
	v_addc_co_u32_e32 v3, vcc, 0, v35, vcc
	global_store_short v[2:3], v1, off

	.amdhsa_kernel _Z4mega6Paramsii
		.amdhsa_group_segment_fixed_size 49168
		.amdhsa_private_segment_fixed_size 0
		.amdhsa_kernarg_size 512
		.amdhsa_user_sgpr_count 2
		.amdhsa_user_sgpr_dispatch_ptr 0
		.amdhsa_user_sgpr_queue_ptr 0
		.amdhsa_user_sgpr_kernarg_segment_ptr 1
		.amdhsa_user_sgpr_dispatch_id 0
		.amdhsa_user_sgpr_kernarg_preload_length 0
		.amdhsa_user_sgpr_kernarg_preload_offset 0
		.amdhsa_user_sgpr_private_segment_size 0
		.amdhsa_uses_dynamic_stack 0
		.amdhsa_enable_private_segment 0
		.amdhsa_system_sgpr_workgroup_id_x 1
		.amdhsa_system_sgpr_workgroup_id_y 0
		.amdhsa_system_sgpr_workgroup_id_z 0
		.amdhsa_system_sgpr_workgroup_info 0
		.amdhsa_system_vgpr_workitem_id 2
		.amdhsa_next_free_vgpr 256
		.amdhsa_next_free_sgpr 102
		.amdhsa_accum_offset 256
		.amdhsa_reserve_vcc 1
		.amdhsa_float_round_mode_32 0
		.amdhsa_float_round_mode_16_64 0
		.amdhsa_float_denorm_mode_32 3
		.amdhsa_float_denorm_mode_16_64 3
		.amdhsa_dx10_clamp 1
		.amdhsa_ieee_mode 1
		.amdhsa_fp16_overflow 0
		.amdhsa_tg_split 0
		.amdhsa_exception_fp_ieee_invalid_op 0
		.amdhsa_exception_fp_denorm_src 0
		.amdhsa_exception_fp_ieee_div_zero 0
		.amdhsa_exception_fp_ieee_overflow 0
		.amdhsa_exception_fp_ieee_underflow 0
		.amdhsa_exception_fp_ieee_inexact 0
		.amdhsa_exception_int_div_zero 0
	.end_amdhsa_kernel

amdhsa.kernels:
  - .agpr_count:     0
    .args:
      - .offset:         0
        .size:           248
        .value_kind:     by_value
      - .offset:         248
        .size:           4
        .value_kind:     by_value
      - .offset:         252
        .size:           4
        .value_kind:     by_value
      - .offset:         256
        .size:           4
        .value_kind:     hidden_block_count_x
      - .offset:         260
        .size:           4
        .value_kind:     hidden_block_count_y
      - .offset:         264
        .size:           4
        .value_kind:     hidden_block_count_z
      - .offset:         268
        .size:           2
        .value_kind:     hidden_group_size_x
      - .offset:         270
        .size:           2
        .value_kind:     hidden_group_size_y
      - .offset:         272
        .size:           2
        .value_kind:     hidden_group_size_z
      - .offset:         274
        .size:           2
        .value_kind:     hidden_remainder_x
      - .offset:         276
        .size:           2
        .value_kind:     hidden_remainder_y
      - .offset:         278
        .size:           2
        .value_kind:     hidden_remainder_z
      - .offset:         296
        .size:           8
        .value_kind:     hidden_global_offset_x
      - .offset:         304
        .size:           8
        .value_kind:     hidden_global_offset_y
      - .offset:         312
        .size:           8
        .value_kind:     hidden_global_offset_z
      - .offset:         320
        .size:           2
        .value_kind:     hidden_grid_dims
      - .offset:         344
        .size:           8
        .value_kind:     hidden_multigrid_sync_arg
    .group_segment_fixed_size: 49168
    .kernarg_segment_align: 8
    .kernarg_segment_size: 512
    .language:       OpenCL C
    .language_version:
      - 2
      - 0
    .max_flat_workgroup_size: 256
    .name:           _Z4mega6Paramsii
    .private_segment_fixed_size: 0
    .sgpr_count:     108
    .sgpr_spill_count: 283
    .symbol:         _Z4mega6Paramsii.kd
    .uniform_work_group_size: 1
    .uses_dynamic_stack: false
    .vgpr_count:     256
    .vgpr_spill_count: 0
    .wavefront_size: 64
